# attention V tile stored with permuted row order (row = dg + 18*e): conflict-free transposed V writes and reads
# speedup vs baseline: 1.0140x; 1.0140x over previous
; template <int DQ, int TYPE>
; __device__ __forceinline__ void attn_item(PP p, int layer, int b, int h, int qt, char* lds, const int tid_, unsigned* next_ctr, volatile XLAS unsigned* slot) {
;     ...
;     A_LSTORE(A, 0); __syncthreads();
;     if (kh == 0) __builtin_amdgcn_s_setprio(2);
; #pragma unroll 1
;     for (int j = j_lo; j <= j_hi; ++j) {
;         const int buf = (j - j_lo) & 1;
;         if (j < j_hi) A_GLOAD(A, j + 1);
;         int mode = 0;
;         if (TYPE == 2) mode = 2;
;         else if (TYPE == 1 && (j >> 2) < own) mode = 3;
;         else if (j >= 2 * qt) mode = 1;
;         const int kbase_pos = 64 * j + 32 * kh;
;         const int qlo = 128 * qt + 32 * qg;
;         bool skip = false;
;         if (mode == 1 || mode == 2) { if (kbase_pos > qlo + 31) skip = true; }
;         if (mode == 2) { if (kbase_pos + 31 <= qlo - 128) skip = true; }
;         if (!skip) {
;             const bf16_t* Ks = (const bf16_t*)(lds + buf * STAGE); const bf16_t* Vt = (const bf16_t*)(lds + buf * STAGE + KBYTES);
.LBB0_400:
	v_lshl_add_u32 v0, v157, 1, 16
	v_mul_lo_u32 v159, v146, s84
	v_add_u32_e32 v4, v0, v159
	v_mul_lo_u32 v160, v148, s84
	s_waitcnt vmcnt(11)
	ds_write_b128 v4, v[96:99]
	v_add_u32_e32 v4, v0, v160
	v_mul_u32_u24_e32 v5, 15, v157
	v_lshlrev_b32_e32 v161, 1, v150
	s_waitcnt vmcnt(10)
	ds_write_b128 v4, v[100:103]
	s_waitcnt vmcnt(9)
	v_and_b32_e32 v4, 0xffff, v116
	v_add3_u32 v0, v0, v5, v161
	v_lshrrev_b32_e32 v5, 16, v116
	s_waitcnt vmcnt(8)
	v_lshl_or_b32 v4, v128, 16, v4
	v_and_or_b32 v5, v128, s91, v5
	v_add_u32_e32 v0, 0x4400, v0
	ds_write_b32 v0, v4
	ds_write_b32 v0, v5 offset:2448
	v_and_b32_e32 v4, 0xffff, v117
	v_lshrrev_b32_e32 v5, 16, v117
	v_lshl_or_b32 v4, v129, 16, v4
	v_and_or_b32 v5, v129, s91, v5
	ds_write_b32 v0, v4 offset:4896
	ds_write_b32 v0, v5 offset:7344
	v_and_b32_e32 v4, 0xffff, v118
	v_lshrrev_b32_e32 v5, 16, v118
	v_lshl_or_b32 v4, v130, 16, v4
	v_and_or_b32 v5, v130, s91, v5
	ds_write_b32 v0, v4 offset:9792
	ds_write_b32 v0, v5 offset:12240
	v_and_b32_e32 v4, 0xffff, v119
	v_lshrrev_b32_e32 v5, 16, v119
	v_lshl_or_b32 v4, v131, 16, v4
	v_and_or_b32 v5, v131, s91, v5
	s_andn2_b64 vcc, exec, s[52:53]
	ds_write_b32 v0, v4 offset:14688
	ds_write_b32 v0, v5 offset:17136
	s_waitcnt lgkmcnt(0)
	s_barrier
	s_cbranch_vccnz .LBB0_402
	s_setprio 2
.LBB0_402:
	s_or_b32 s13, s51, 1
	s_ashr_i32 s56, s16, 8
	s_cmp_gt_i32 s12, s13
	v_lshlrev_b32_e32 v155, 2, v3
	s_cbranch_scc1 .LBB0_413
	s_lshl_b32 s13, s56, 5
	v_or_b32_e32 v0, s13, v2
	s_add_i32 s16, s15, 0xf65
	v_mul_lo_u32 v163, v0, s84
	v_add_u32_e32 v0, s16, v2
	s_lshl_b32 s16, s12, 6
	s_add_i32 s59, s16, s13
	v_lshlrev_b32_e32 v16, 3, v3
	v_or_b32_e32 v3, s59, v155
	v_sub_u32_e32 v0, v0, v3
	s_lshl_b32 s14, s14, 7
	v_subrev_u32_e32 v165, s14, v0
	s_add_i32 s14, s14, s59
	s_addk_i32 s14, 0xf080
	v_or_b32_e32 v0, s14, v155
	v_sub_u32_e32 v0, v0, v2
	v_mov_b32_e32 v14, v1
	v_mov_b32_e32 v15, v1
	v_and_b32_e32 v244, 7, v2
	v_lshrrev_b32_e32 v245, 3, v2
	v_mad_u32_u24 v244, v244, 18, v245
	v_mul_u32_u24_e32 v164, 0x88, v244
	v_subrev_u32_e32 v166, s15, v0
	v_mov_b32_e32 v0, v1
	v_mov_b32_e32 v2, v1
	v_mov_b32_e32 v3, v1
	v_mov_b32_e32 v4, v1
	v_mov_b32_e32 v5, v1
	v_mov_b32_e32 v6, v1
	v_mov_b32_e32 v7, v1
	v_mov_b32_e32 v8, v1
	v_mov_b32_e32 v9, v1
	v_mov_b32_e32 v10, v1
	v_mov_b32_e32 v11, v1
	v_mov_b32_e32 v12, v1
	v_mov_b32_e32 v13, v1
	v_lshlrev_b32_e32 v167, 1, v16
	v_mov_b64_e32 v[46:47], v[14:15]
	v_mov_b64_e32 v[30:31], v[14:15]
	v_mov_b64_e32 v[78:79], v[14:15]
	v_mov_b64_e32 v[62:63], v[14:15]
	v_mul_u32_u24_e32 v162, 17, v157
	s_or_b32 s57, s58, 31
	s_addk_i32 s58, 0xff80
	v_mov_b64_e32 v[44:45], v[12:13]
	v_mov_b64_e32 v[42:43], v[10:11]
	v_mov_b64_e32 v[40:41], v[8:9]
	v_mov_b64_e32 v[38:39], v[6:7]
	v_mov_b64_e32 v[36:37], v[4:5]
	v_mov_b64_e32 v[34:35], v[2:3]
	v_mov_b64_e32 v[32:33], v[0:1]
	v_mov_b64_e32 v[28:29], v[12:13]
	v_mov_b64_e32 v[26:27], v[10:11]
	v_mov_b64_e32 v[24:25], v[8:9]
	v_mov_b64_e32 v[22:23], v[6:7]
	v_mov_b64_e32 v[20:21], v[4:5]
	v_mov_b64_e32 v[18:19], v[2:3]
	v_mov_b64_e32 v[16:17], v[0:1]
	v_mov_b64_e32 v[76:77], v[12:13]
	v_mov_b64_e32 v[74:75], v[10:11]
	v_mov_b64_e32 v[72:73], v[8:9]
	v_mov_b64_e32 v[70:71], v[6:7]
	v_mov_b64_e32 v[68:69], v[4:5]
	v_mov_b64_e32 v[66:67], v[2:3]
	v_mov_b64_e32 v[64:65], v[0:1]
	v_mov_b64_e32 v[60:61], v[12:13]
	v_mov_b64_e32 v[58:59], v[10:11]
	v_mov_b64_e32 v[56:57], v[8:9]
	v_mov_b64_e32 v[54:55], v[6:7]
	v_mov_b64_e32 v[52:53], v[4:5]
	v_mov_b64_e32 v[50:51], v[2:3]
	v_mov_b64_e32 v[48:49], v[0:1]
	s_waitcnt vmcnt(0)
	s_branch .LBB0_406
.LBB0_404:
	s_xor_b32 s16, s60, 1
	s_mul_i32 s16, s16, 0x8f70
	s_add_i32 s16, s16, 16
	v_lshl_add_u32 v0, v157, 1, s16
	v_add_u32_e32 v2, v0, v159
	v_add_u32_e32 v0, v0, v160
	s_waitcnt vmcnt(3)
	ds_write_b128 v2, v[96:99]
	s_waitcnt vmcnt(2)
	ds_write_b128 v0, v[100:103]
	s_waitcnt vmcnt(1)
	v_and_b32_e32 v0, 0xffff, v116
	v_add3_u32 v2, s16, v162, v161
	v_lshrrev_b32_e32 v3, 16, v116
	s_waitcnt vmcnt(0)
	v_lshl_or_b32 v0, v128, 16, v0
	v_and_or_b32 v3, v128, s91, v3
	v_add_u32_e32 v2, 0x4400, v2
	ds_write_b32 v2, v0
	ds_write_b32 v2, v3 offset:2448
	v_and_b32_e32 v0, 0xffff, v117
	v_lshrrev_b32_e32 v3, 16, v117
	v_lshl_or_b32 v0, v129, 16, v0
	v_and_or_b32 v3, v129, s91, v3
	ds_write_b32 v2, v0 offset:4896
	ds_write_b32 v2, v3 offset:7344
	v_and_b32_e32 v0, 0xffff, v118
	v_lshrrev_b32_e32 v3, 16, v118
	v_lshl_or_b32 v0, v130, 16, v0
	v_and_or_b32 v3, v130, s91, v3
	ds_write_b32 v2, v0 offset:9792
	ds_write_b32 v2, v3 offset:12240
	v_and_b32_e32 v0, 0xffff, v119
	v_lshrrev_b32_e32 v3, 16, v119
	v_lshl_or_b32 v0, v131, 16, v0
	v_and_or_b32 v3, v131, s91, v3
	ds_write_b32 v2, v0 offset:14688
	ds_write_b32 v2, v3 offset:17136

; template <int DQ, int TYPE>
; __device__ __forceinline__ void attn_item(PP p, int layer, int b, int h, int qt, char* lds, const int tid_, unsigned* next_ctr, volatile XLAS unsigned* slot) {
;     ...
;         if (!skip) {
;             const bf16_t* Ks = (const bf16_t*)(lds + buf * STAGE); const bf16_t* Vt = (const bf16_t*)(lds + buf * STAGE + KBYTES);
;             f32x16 sacc;
; #pragma unroll
;             for (int i = 0; i < 16; ++i) sacc[i] = 0.f;
;             const bf16_t* kb_ = Ks + (32 * kh + r) * KLD + 8 * hh;
;             bf16x8 kf[2][GK];
; #pragma unroll
;             for (int i = 0; i < GK; ++i) kf[0][i] = *(const bf16x8*)(kb_ + 16 * i);
; #pragma unroll
;             for (int g = 0; g < NG; ++g) {
;                 if (g + 1 < NG) {
; #pragma unroll
;                     for (int i = 0; i < GK; ++i) kf[(g + 1) & 1][i] = *(const bf16x8*)(kb_ + 16 * ((g + 1) * GK + i));
;                 }
;                 __builtin_amdgcn_sched_barrier(0);
; #pragma unroll
;                 for (int i = 0; i < GK; ++i) sacc = __builtin_amdgcn_mfma_f32_32x32x16_bf16(kf[g & 1][i], qf[g * GK + i], sacc, 0, 0, 0);
;                 __builtin_amdgcn_sched_barrier(0);
;             }
;             const bf16_t* vb0 = Vt + r * VLD + 32 * kh + 4 * hh;
;             u32x2 vf[2][4][2];
; #pragma unroll
;             for (int md = 0; md < 4; ++md) { vf[0][md][0] = *(const u32x2*)(vb0 + md * 32 * VLD); vf[0][md][1] = *(const u32x2*)(vb0 + md * 32 * VLD + 8); }
;     ...
;             for (int s2 = 0; s2 < 2; ++s2) {
;                 if (s2 == 0) {
; #pragma unroll
;                     for (int md = 0; md < 4; ++md) { vf[1][md][0] = *(const u32x2*)(vb0 + 16 + md * 32 * VLD); vf[1][md][1] = *(const u32x2*)(vb0 + 16 + md * 32 * VLD + 8); }
;                 }
.LBB0_408:
	s_and_b32 s60, s12, 1
	s_cmp_gt_i32 s59, s57
	s_cselect_b64 s[62:63], -1, 0
	s_add_i32 s61, s59, 31
	s_cmp_le_i32 s61, s58
	s_cselect_b64 s[64:65], -1, 0
	s_or_b64 s[62:63], s[64:65], s[62:63]
	s_and_b64 vcc, exec, s[62:63]
	s_cbranch_vccnz .LBB0_412
	s_mul_i32 s61, s60, 0x8f70
	s_add_i32 s61, s61, 16
	v_add3_u32 v0, s61, v163, v167
	ds_read_b128 v[2:5], v0
	ds_read_b128 v[6:9], v0 offset:32
	ds_read_b128 v[10:13], v0 offset:64
	ds_read_b128 v[170:173], v0 offset:96
	ds_read_b128 v[174:177], v0 offset:128
	ds_read_b128 v[190:193], v0 offset:160
	ds_read_b128 v[194:197], v0 offset:192
	ds_read_b128 v[198:201], v0 offset:224
	s_waitcnt lgkmcnt(7)
	v_mfma_f32_32x32x16_bf16 v[80:95], v[2:5], v[104:107], 0
	s_waitcnt lgkmcnt(6)
	v_mfma_f32_32x32x16_bf16 v[80:95], v[6:9], v[108:111], v[80:95]
	s_waitcnt lgkmcnt(5)
	v_mfma_f32_32x32x16_bf16 v[80:95], v[10:13], v[112:115], v[80:95]
	s_waitcnt lgkmcnt(4)
	v_mfma_f32_32x32x16_bf16 v[80:95], v[170:173], v[120:123], v[80:95]
	s_waitcnt lgkmcnt(3)
	v_mfma_f32_32x32x16_bf16 v[80:95], v[174:177], v[124:127], v[80:95]
	s_lshl_b32 s62, s13, 1
	v_add_u32_e32 v10, 27, v165
	s_add_i32 s62, s62, s61
	v_cmp_gt_u32_e32 vcc, s42, v10
	s_movk_i32 s61, 0xff7f
	v_add_u32_e32 v11, 25, v165
	v_add_u32_e32 v12, 24, v165
	s_waitcnt lgkmcnt(2)
	v_mfma_f32_32x32x16_bf16 v[80:95], v[190:193], v[132:135], v[80:95]
	v_add_u32_e32 v13, 19, v165
	v_add_u32_e32 v14, 18, v165
	v_add_u32_e32 v175, 17, v165
	v_add_u32_e32 v176, 16, v165
	v_add_u32_e32 v10, 11, v165
	v_lshlrev_b32_e32 v0, 1, v155
	v_add3_u32 v0, s62, v164, v0
	s_waitcnt lgkmcnt(1)
	v_mfma_f32_32x32x16_bf16 v[80:95], v[194:197], v[136:139], v[80:95]
	v_add_u32_e32 v169, 0x4000, v0
	v_add_u32_e32 v15, 0x4120, v0
	ds_read2_b64 v[2:5], v169 offset0:128 offset1:130
	ds_read2_b64 v[6:9], v15 offset0:160 offset1:162
	s_waitcnt lgkmcnt(2)
	v_mfma_f32_32x32x16_bf16 v[80:95], v[198:201], v[140:143], v[80:95]
	s_nop 11
	v_cndmask_b32_e32 v170, v225, v80, vcc
	v_cmp_lt_u32_e32 vcc, s61, v166
	s_nop 1
	v_cndmask_b32_e32 v172, v225, v81, vcc
	v_cmp_gt_u32_e32 vcc, s42, v11
	s_nop 1
	v_cndmask_b32_e32 v173, v225, v82, vcc
	v_cmp_gt_u32_e32 vcc, s42, v12
	v_max_f32_e32 v11, v173, v173
	s_nop 0
	v_cndmask_b32_e32 v174, v225, v83, vcc
	v_cmp_gt_u32_e32 vcc, s42, v13
	s_nop 1
	v_cndmask_b32_e32 v171, v225, v84, vcc
	v_cmp_gt_u32_e32 vcc, s42, v14
	v_max_f32_e32 v12, v171, v171
	s_nop 0
	v_cndmask_b32_e32 v85, v225, v85, vcc
	v_cmp_gt_u32_e32 vcc, s42, v175
	s_nop 1
	v_cndmask_b32_e32 v177, v225, v86, vcc
	v_cmp_gt_u32_e32 vcc, s42, v176
	v_max_f32_e32 v13, v177, v177
	s_nop 0
	v_cndmask_b32_e32 v176, v225, v87, vcc
	v_cmp_gt_u32_e32 vcc, s42, v10
	v_add_u32_e32 v10, 10, v165
	s_nop 0
	v_cndmask_b32_e32 v175, v225, v88, vcc
	v_cmp_gt_u32_e32 vcc, s42, v10
	v_add_u32_e32 v10, 9, v165
	s_nop 0
	v_cndmask_b32_e32 v89, v225, v89, vcc
	v_cmp_gt_u32_e32 vcc, s42, v10
	v_add_u32_e32 v10, 8, v165
	s_nop 0
	v_cndmask_b32_e32 v90, v225, v90, vcc
	v_cmp_gt_u32_e32 vcc, s42, v10
	v_add_u32_e32 v10, 3, v165
	s_nop 0
	v_cndmask_b32_e32 v91, v225, v91, vcc
	v_cmp_gt_u32_e32 vcc, s42, v10
	v_add_u32_e32 v10, 2, v165
	s_nop 0
	v_cndmask_b32_e32 v86, v225, v92, vcc
	v_cmp_gt_u32_e32 vcc, s42, v10
	v_add_u32_e32 v10, 1, v165
	v_add_u32_e32 v92, 0x4360, v0
	v_cndmask_b32_e32 v87, v225, v93, vcc
	v_cmp_gt_u32_e32 vcc, s42, v10
	v_max_f32_e32 v10, v174, v174
	v_max_f32_e32 v10, v11, v10
	v_max_f32_e32 v11, v85, v85
	v_max_f32_e32 v11, v12, v11
	v_max_f32_e32 v12, v176, v176
	v_max3_f32 v10, v170, v172, v10
	v_max_f32_e32 v12, v13, v12
	v_max3_f32 v10, v10, v11, v12
	v_max_f32_e32 v11, v89, v89
	v_max_f32_e32 v12, v175, v175
	v_max_f32_e32 v11, v12, v11
	v_max_f32_e32 v12, v91, v91
	v_max_f32_e32 v13, v90, v90
	v_cndmask_b32_e32 v88, v225, v94, vcc
	v_cmp_gt_u32_e32 vcc, s42, v165
	v_max_f32_e32 v12, v13, v12
	v_max3_f32 v10, v10, v11, v12
	v_cndmask_b32_e32 v84, v225, v95, vcc
	v_max_f32_e32 v11, v87, v87
	v_max_f32_e32 v12, v86, v86
	v_max_f32_e32 v11, v12, v11
	v_max_f32_e32 v12, v84, v84
	v_max_f32_e32 v13, v88, v88
	v_max_f32_e32 v12, v13, v12
	v_max3_f32 v10, v10, v11, v12
	v_mul_f32_e32 v14, 0x3e0293ee, v10
	v_add_u32_e32 v93, 0x4240, v0
	ds_read2_b64 v[80:83], v93 offset0:192 offset1:194
	v_mov_b32_e32 v94, v14
	ds_read2_b64 v[10:13], v92 offset0:224 offset1:226
	s_nop 1
	v_permlane32_swap_b32_e32 v94, v14
	v_max_f32_e32 v94, v14, v94
	v_add_f32_e32 v0, 0x41000000, v168
	v_cmp_gt_f32_e32 vcc, v94, v0
	s_nop 1
	v_cndmask_b32_e32 v14, v168, v94, vcc
	v_sub_f32_e32 v0, v168, v14
	v_exp_f32_e32 v0, v0
	s_cbranch_vccz .LBB0_411
	v_pk_mul_f32 v[46:47], v[46:47], v[0:1] op_sel_hi:[1,0]
	v_pk_mul_f32 v[44:45], v[44:45], v[0:1] op_sel_hi:[1,0]
	v_pk_mul_f32 v[42:43], v[42:43], v[0:1] op_sel_hi:[1,0]
	v_pk_mul_f32 v[40:41], v[40:41], v[0:1] op_sel_hi:[1,0]
	v_pk_mul_f32 v[38:39], v[38:39], v[0:1] op_sel_hi:[1,0]
	v_pk_mul_f32 v[36:37], v[36:37], v[0:1] op_sel_hi:[1,0]
	v_pk_mul_f32 v[34:35], v[34:35], v[0:1] op_sel_hi:[1,0]
	v_pk_mul_f32 v[32:33], v[32:33], v[0:1] op_sel_hi:[1,0]
	v_pk_mul_f32 v[30:31], v[30:31], v[0:1] op_sel_hi:[1,0]
	v_pk_mul_f32 v[28:29], v[28:29], v[0:1] op_sel_hi:[1,0]
	v_pk_mul_f32 v[26:27], v[26:27], v[0:1] op_sel_hi:[1,0]
	v_pk_mul_f32 v[24:25], v[24:25], v[0:1] op_sel_hi:[1,0]
	v_pk_mul_f32 v[22:23], v[22:23], v[0:1] op_sel_hi:[1,0]
	v_pk_mul_f32 v[20:21], v[20:21], v[0:1] op_sel_hi:[1,0]
	v_pk_mul_f32 v[18:19], v[18:19], v[0:1] op_sel_hi:[1,0]
	v_pk_mul_f32 v[16:17], v[16:17], v[0:1] op_sel_hi:[1,0]
	v_pk_mul_f32 v[78:79], v[78:79], v[0:1] op_sel_hi:[1,0]
	v_pk_mul_f32 v[76:77], v[76:77], v[0:1] op_sel_hi:[1,0]
	v_pk_mul_f32 v[74:75], v[74:75], v[0:1] op_sel_hi:[1,0]
	v_pk_mul_f32 v[72:73], v[72:73], v[0:1] op_sel_hi:[1,0]
	v_pk_mul_f32 v[70:71], v[70:71], v[0:1] op_sel_hi:[1,0]
	v_pk_mul_f32 v[68:69], v[68:69], v[0:1] op_sel_hi:[1,0]
	v_pk_mul_f32 v[66:67], v[66:67], v[0:1] op_sel_hi:[1,0]
	v_pk_mul_f32 v[64:65], v[64:65], v[0:1] op_sel_hi:[1,0]
	v_pk_mul_f32 v[62:63], v[62:63], v[0:1] op_sel_hi:[1,0]
	v_pk_mul_f32 v[60:61], v[60:61], v[0:1] op_sel_hi:[1,0]
	v_pk_mul_f32 v[58:59], v[58:59], v[0:1] op_sel_hi:[1,0]
	v_pk_mul_f32 v[56:57], v[56:57], v[0:1] op_sel_hi:[1,0]
	v_pk_mul_f32 v[54:55], v[54:55], v[0:1] op_sel_hi:[1,0]
	v_pk_mul_f32 v[52:53], v[52:53], v[0:1] op_sel_hi:[1,0]
	v_pk_mul_f32 v[50:51], v[50:51], v[0:1] op_sel_hi:[1,0]
	v_pk_mul_f32 v[48:49], v[48:49], v[0:1] op_sel_hi:[1,0]

; template <int DQ, int TYPE>
; __device__ __forceinline__ void attn_item(PP p, int layer, int b, int h, int qt, char* lds, const int tid_, unsigned* next_ctr, volatile XLAS unsigned* slot) {
;     ...
;     A_LSTORE(A, 0); __syncthreads();
.LBB0_635:
	v_lshl_add_u32 v2, v185, 1, 16
	v_mul_lo_u32 v158, v166, s84
	v_add_u32_e32 v3, v2, v158
	v_mul_lo_u32 v159, v168, s84
	s_waitcnt vmcnt(11)
	ds_write_b128 v3, v[82:85]
	v_add_u32_e32 v3, v2, v159
	v_mul_u32_u24_e32 v4, 15, v185
	v_lshlrev_b32_e32 v160, 1, v170
	s_waitcnt vmcnt(10)
	ds_write_b128 v3, v[86:89]
	s_waitcnt vmcnt(9)
	v_and_b32_e32 v3, 0xffff, v106
	v_add3_u32 v2, v2, v4, v160
	v_lshrrev_b32_e32 v4, 16, v106
	s_waitcnt vmcnt(8)
	v_lshl_or_b32 v3, v118, 16, v3
	v_and_or_b32 v4, v118, s91, v4
	v_add_u32_e32 v2, 0x4400, v2
	ds_write_b32 v2, v3
	ds_write_b32 v2, v4 offset:2448
	v_and_b32_e32 v3, 0xffff, v107
	v_lshrrev_b32_e32 v4, 16, v107
	s_lshl_b32 s56, s96, 12
	s_lshl_b32 s55, s97, 7
	v_lshl_or_b32 v3, v119, 16, v3
	v_and_or_b32 v4, v119, s91, v4
	ds_write_b32 v2, v3 offset:4896
	ds_write_b32 v2, v4 offset:7344
	v_and_b32_e32 v3, 0xffff, v108
	v_lshrrev_b32_e32 v4, 16, v108
	s_cmpk_lt_u32 s88, 0x100
	v_lshl_or_b32 v3, v120, 16, v3
	v_and_or_b32 v4, v120, s91, v4
	s_cselect_b64 s[52:53], -1, 0
	s_cmpk_gt_u32 s88, 0xff
	ds_write_b32 v2, v3 offset:9792
	ds_write_b32 v2, v4 offset:12240
	v_and_b32_e32 v3, 0xffff, v109
	v_lshrrev_b32_e32 v4, 16, v109
	s_cselect_b64 s[8:9], -1, 0
	v_lshl_or_b32 v3, v121, 16, v3
	v_and_or_b32 v4, v121, s91, v4
	s_and_b64 vcc, exec, s[8:9]
	ds_write_b32 v2, v3 offset:14688
	ds_write_b32 v2, v4 offset:17136
	s_waitcnt lgkmcnt(0)
	s_barrier
	s_cbranch_vccnz .LBB0_637
	s_setprio 2
.LBB0_637:
	s_waitcnt vmcnt(0)
	s_ashr_i32 s54, s88, 8
	s_lshl_b32 s58, s54, 5
	v_or_b32_e32 v2, s58, v154
	v_mov_b32_e32 v18, v1
	v_mov_b32_e32 v19, v1
	v_mov_b32_e32 v32, v1
	v_mov_b32_e32 v33, v1
	v_mul_lo_u32 v162, v2, s84
	s_lshl_b32 s12, s49, 1
	v_mov_b32_e32 v20, v1
	v_mov_b32_e32 v21, v1
	v_mov_b32_e32 v22, v1
	v_mov_b32_e32 v23, v1
	v_mov_b32_e32 v24, v1
	v_mov_b32_e32 v25, v1
	v_mov_b32_e32 v26, v1
	v_mov_b32_e32 v27, v1
	v_mov_b32_e32 v28, v1
	v_mov_b32_e32 v29, v1
	v_mov_b32_e32 v30, v1
	v_mov_b32_e32 v31, v1
	v_mov_b64_e32 v[2:3], v[18:19]
	v_mov_b64_e32 v[64:65], v[32:33]
	v_mov_b64_e32 v[48:49], v[32:33]
	v_mul_u32_u24_e32 v161, 17, v185
	s_lshl_b32 s57, s80, 1
	s_or_b32 s59, s95, 31
	v_and_b32_e32 v244, 7, v154
	v_lshrrev_b32_e32 v245, 3, v154
	v_mad_u32_u24 v244, v244, 18, v245
	v_mul_u32_u24_e32 v163, 0x88, v244
	v_lshlrev_b32_e32 v147, 2, v155
	s_sub_i32 s60, 64, s12
	s_mov_b32 s61, 0
	v_mov_b32_e32 v164, 0
	v_mov_b32_e32 v176, 0xf149f2ca
	s_mov_b32 s62, s58
	v_mov_b64_e32 v[4:5], v[20:21]
	v_mov_b64_e32 v[6:7], v[22:23]
	v_mov_b64_e32 v[8:9], v[24:25]
	v_mov_b64_e32 v[10:11], v[26:27]
	v_mov_b64_e32 v[12:13], v[28:29]
	v_mov_b64_e32 v[14:15], v[30:31]
	v_mov_b64_e32 v[16:17], v[32:33]
	v_mov_b64_e32 v[62:63], v[30:31]
	v_mov_b64_e32 v[60:61], v[28:29]
	v_mov_b64_e32 v[58:59], v[26:27]
	v_mov_b64_e32 v[56:57], v[24:25]
	v_mov_b64_e32 v[54:55], v[22:23]
	v_mov_b64_e32 v[52:53], v[20:21]
	v_mov_b64_e32 v[50:51], v[18:19]
	v_mov_b64_e32 v[46:47], v[30:31]
	v_mov_b64_e32 v[44:45], v[28:29]
	v_mov_b64_e32 v[42:43], v[26:27]
	v_mov_b64_e32 v[40:41], v[24:25]
	v_mov_b64_e32 v[38:39], v[22:23]
	v_mov_b64_e32 v[36:37], v[20:21]
	v_mov_b64_e32 v[34:35], v[18:19]
	s_cmp_le_u32 s61, s57
	s_cselect_b64 s[12:13], -1, 0
	s_cmp_gt_u32 s61, s57
	s_cbranch_scc1 .LBB0_640
	s_branch .LBB0_639

; template <int DQ, int TYPE>
; __device__ __forceinline__ void attn_item(PP p, int layer, int b, int h, int qt, char* lds, const int tid_, unsigned* next_ctr, volatile XLAS unsigned* slot) {
;     ...
;         if (!skip) {
;             const bf16_t* Ks = (const bf16_t*)(lds + buf * STAGE); const bf16_t* Vt = (const bf16_t*)(lds + buf * STAGE + KBYTES);
;             f32x16 sacc;
; #pragma unroll
;             for (int i = 0; i < 16; ++i) sacc[i] = 0.f;
;             const bf16_t* kb_ = Ks + (32 * kh + r) * KLD + 8 * hh;
;             bf16x8 kf[2][GK];
; #pragma unroll
;             for (int i = 0; i < GK; ++i) kf[0][i] = *(const bf16x8*)(kb_ + 16 * i);
; #pragma unroll
;             for (int g = 0; g < NG; ++g) {
;                 if (g + 1 < NG) {
; #pragma unroll
;                     for (int i = 0; i < GK; ++i) kf[(g + 1) & 1][i] = *(const bf16x8*)(kb_ + 16 * ((g + 1) * GK + i));
;                 }
;                 __builtin_amdgcn_sched_barrier(0);
; #pragma unroll
;                 for (int i = 0; i < GK; ++i) sacc = __builtin_amdgcn_mfma_f32_32x32x16_bf16(kf[g & 1][i], qf[g * GK + i], sacc, 0, 0, 0);
;                 __builtin_amdgcn_sched_barrier(0);
;             }
;             const bf16_t* vb0 = Vt + r * VLD + 32 * kh + 4 * hh;
;             u32x2 vf[2][4][2];
; #pragma unroll
;             for (int md = 0; md < 4; ++md) { vf[0][md][0] = *(const u32x2*)(vb0 + md * 32 * VLD); vf[0][md][1] = *(const u32x2*)(vb0 + md * 32 * VLD + 8); }
;             if (mode != 0) {
;                 const bool selbit = (qmask >> (j >> 2)) & 1u;
; #pragma unroll
;                 for (int i = 0; i < 16; ++i) {
;                     const int kpos = kbase_pos + 8 * (i >> 2) + 4 * hh + (i & 3);
;                     const int dd = qpos - kpos;
;                     bool ok;
;                     if (mode == 1) ok = dd >= 0; else if (mode == 2) ok = (dd >= 0 && dd < 128); else ok = selbit;
;                     if (!ok) sacc[i] = -INFINITY;
;                 }
;             }
.LBB0_640:
	s_and_b32 s63, s61, 1
	s_lshr_b32 s64, s61, 2
	s_cmp_ge_u32 s64, s94
	s_cselect_b64 s[14:15], -1, 0
	s_cmp_lt_u32 s61, s57
	s_cselect_b64 s[16:17], -1, 0
	s_cmp_ge_u32 s61, s57
	s_cselect_b64 s[50:51], -1, 0
	s_and_b64 s[50:51], s[14:15], s[50:51]
	s_cmp_gt_i32 s62, s59
	s_cselect_b64 s[66:67], -1, 0
	s_and_b64 s[66:67], s[50:51], s[66:67]
	s_and_b64 vcc, exec, s[66:67]
	s_cbranch_vccnz .LBB0_646
	s_and_b64 s[14:15], s[14:15], s[16:17]
	s_mul_i32 s16, s63, 0x8f70
	s_add_i32 s16, s16, 16
	v_lshlrev_b32_e32 v66, 1, v153
	v_add3_u32 v70, s16, v162, v66
	ds_read_b128 v[66:69], v70
	ds_read_b128 v[130:133], v70 offset:32
	ds_read_b128 v[134:137], v70 offset:64
	ds_read_b128 v[138:141], v70 offset:96
	ds_read_b128 v[142:145], v70 offset:128
	ds_read_b128 v[172:175], v70 offset:160
	ds_read_b128 v[190:193], v70 offset:192
	ds_read_b128 v[194:197], v70 offset:224
	s_waitcnt lgkmcnt(7)
	v_mfma_f32_32x32x16_bf16 v[66:81], v[66:69], v[90:93], 0
	s_waitcnt lgkmcnt(6)
	v_mfma_f32_32x32x16_bf16 v[66:81], v[130:133], v[94:97], v[66:81]
	s_waitcnt lgkmcnt(5)
	v_mfma_f32_32x32x16_bf16 v[66:81], v[134:137], v[98:101], v[66:81]
	s_waitcnt lgkmcnt(4)
	v_mfma_f32_32x32x16_bf16 v[66:81], v[138:141], v[102:105], v[66:81]
	s_waitcnt lgkmcnt(3)
	v_mfma_f32_32x32x16_bf16 v[66:81], v[142:145], v[110:113], v[66:81]
	s_lshl_b32 s17, s58, 1
	s_add_i32 s17, s17, s16
	v_lshlrev_b32_e32 v130, 1, v147
	v_add3_u32 v130, s17, v163, v130
	s_and_b64 vcc, exec, s[14:15]
	s_waitcnt lgkmcnt(2)
	v_mfma_f32_32x32x16_bf16 v[66:81], v[172:175], v[114:117], v[66:81]
	v_add_u32_e32 v173, 0x4000, v130
	v_add_u32_e32 v175, 0x4120, v130
	v_add_u32_e32 v174, 0x4240, v130
	v_add_u32_e32 v172, 0x4360, v130
	ds_read2_b64 v[142:145], v173 offset0:128 offset1:130
	ds_read2_b64 v[138:141], v175 offset0:160 offset1:162
	ds_read2_b64 v[134:137], v174 offset0:192 offset1:194
	s_waitcnt lgkmcnt(4)
	v_mfma_f32_32x32x16_bf16 v[66:81], v[190:193], v[122:125], v[66:81]
	ds_read2_b64 v[130:133], v172 offset0:224 offset1:226
	s_waitcnt lgkmcnt(4)
	v_mfma_f32_32x32x16_bf16 v[66:81], v[194:197], v[126:129], v[66:81]
	s_cbranch_vccnz .LBB0_643
	v_add_u32_e32 v165, s62, v147
	v_cmp_ge_i32_e32 vcc, v0, v165
	v_lshrrev_b32_e32 v152, s64, v157
	s_nop 0
	v_cndmask_b32_e64 v177, 0, 1, vcc
	v_cndmask_b32_e64 v177, v152, v177, s[50:51]
	v_and_b32_e32 v177, 1, v177
	v_cmp_eq_u32_e32 vcc, 1, v177
	s_nop 2
	v_cndmask_b32_e32 v66, v225, v66, vcc
	v_cmp_gt_i32_e32 vcc, v0, v165
	s_nop 1
	v_cndmask_b32_e64 v177, 0, 1, vcc
	v_cndmask_b32_e64 v177, v152, v177, s[50:51]
	v_and_b32_e32 v177, 1, v177
	v_cmp_eq_u32_e32 vcc, 1, v177
	v_add_u32_e32 v177, 2, v165
	s_nop 0
	v_cndmask_b32_e32 v67, v225, v67, vcc
	v_cmp_ge_i32_e32 vcc, v0, v177
	s_nop 1
	v_cndmask_b32_e64 v177, 0, 1, vcc
	v_cndmask_b32_e64 v177, v152, v177, s[50:51]
	v_and_b32_e32 v177, 1, v177
	v_cmp_eq_u32_e32 vcc, 1, v177
	v_add_u32_e32 v177, 3, v165
	s_nop 0
	v_cndmask_b32_e32 v68, v225, v68, vcc
	v_cmp_ge_i32_e32 vcc, v0, v177
	s_nop 1
	v_cndmask_b32_e64 v177, 0, 1, vcc
	v_cndmask_b32_e64 v177, v152, v177, s[50:51]
	v_and_b32_e32 v177, 1, v177
	v_cmp_eq_u32_e32 vcc, 1, v177
	v_add_u32_e32 v177, 8, v165
	s_nop 0
	v_cndmask_b32_e32 v69, v225, v69, vcc
	v_cmp_ge_i32_e32 vcc, v0, v177
	s_nop 1
	v_cndmask_b32_e64 v177, 0, 1, vcc
	v_cndmask_b32_e64 v177, v152, v177, s[50:51]
	v_and_b32_e32 v177, 1, v177
	v_cmp_eq_u32_e32 vcc, 1, v177
	v_add_u32_e32 v177, 9, v165
	s_nop 0
	v_cndmask_b32_e32 v70, v225, v70, vcc
	v_cmp_ge_i32_e32 vcc, v0, v177
	s_nop 1
	v_cndmask_b32_e64 v177, 0, 1, vcc
	v_cndmask_b32_e64 v177, v152, v177, s[50:51]
	v_and_b32_e32 v177, 1, v177
	v_cmp_eq_u32_e32 vcc, 1, v177
	v_add_u32_e32 v177, 10, v165
	s_nop 0
	v_cndmask_b32_e32 v71, v225, v71, vcc
	v_cmp_ge_i32_e32 vcc, v0, v177
	s_nop 1
	v_cndmask_b32_e64 v177, 0, 1, vcc
	v_cndmask_b32_e64 v177, v152, v177, s[50:51]
	v_and_b32_e32 v177, 1, v177
	v_cmp_eq_u32_e32 vcc, 1, v177
	v_add_u32_e32 v177, 11, v165
	s_nop 0
	v_cndmask_b32_e32 v72, v225, v72, vcc
	v_cmp_ge_i32_e32 vcc, v0, v177
	s_nop 1
	v_cndmask_b32_e64 v177, 0, 1, vcc
	v_cndmask_b32_e64 v177, v152, v177, s[50:51]
	v_and_b32_e32 v177, 1, v177
	v_cmp_eq_u32_e32 vcc, 1, v177
	v_add_u32_e32 v177, 16, v165
	s_nop 0
	v_cndmask_b32_e32 v73, v225, v73, vcc
	v_cmp_ge_i32_e32 vcc, v0, v177
	s_nop 1
	v_cndmask_b32_e64 v177, 0, 1, vcc
	v_cndmask_b32_e64 v177, v152, v177, s[50:51]
	v_and_b32_e32 v177, 1, v177
	v_cmp_eq_u32_e32 vcc, 1, v177
	v_add_u32_e32 v177, 17, v165
	s_nop 0
	v_cndmask_b32_e32 v74, v225, v74, vcc
	v_cmp_ge_i32_e32 vcc, v0, v177
	s_nop 1
	v_cndmask_b32_e64 v177, 0, 1, vcc
	v_cndmask_b32_e64 v177, v152, v177, s[50:51]
	v_and_b32_e32 v177, 1, v177
	v_cmp_eq_u32_e32 vcc, 1, v177
	v_add_u32_e32 v177, 18, v165
	s_nop 0
	v_cndmask_b32_e32 v75, v225, v75, vcc
	v_cmp_ge_i32_e32 vcc, v0, v177
	s_nop 1
	v_cndmask_b32_e64 v177, 0, 1, vcc
	v_cndmask_b32_e64 v177, v152, v177, s[50:51]
	v_and_b32_e32 v177, 1, v177
	v_cmp_eq_u32_e32 vcc, 1, v177
	v_add_u32_e32 v177, 19, v165
	s_nop 0
	v_cndmask_b32_e32 v76, v225, v76, vcc
	v_cmp_ge_i32_e32 vcc, v0, v177
	s_nop 1
	v_cndmask_b32_e64 v177, 0, 1, vcc
	v_cndmask_b32_e64 v177, v152, v177, s[50:51]
	v_and_b32_e32 v177, 1, v177
	v_cmp_eq_u32_e32 vcc, 1, v177
	v_add_u32_e32 v177, 24, v165
	s_nop 0
	v_cndmask_b32_e32 v77, v225, v77, vcc
	v_cmp_ge_i32_e32 vcc, v0, v177
	s_nop 1
	v_cndmask_b32_e64 v177, 0, 1, vcc
	v_cndmask_b32_e64 v177, v152, v177, s[50:51]
	v_and_b32_e32 v177, 1, v177
	v_cmp_eq_u32_e32 vcc, 1, v177
	v_add_u32_e32 v177, 25, v165
	s_nop 0
	v_cndmask_b32_e32 v78, v225, v78, vcc
	v_cmp_ge_i32_e32 vcc, v0, v177
	s_nop 1
	v_cndmask_b32_e64 v177, 0, 1, vcc
	v_cndmask_b32_e64 v177, v152, v177, s[50:51]
	v_and_b32_e32 v177, 1, v177
	v_cmp_eq_u32_e32 vcc, 1, v177
	v_add_u32_e32 v177, 26, v165
	v_add_u32_e32 v165, 27, v165
	v_cndmask_b32_e32 v79, v225, v79, vcc
	v_cmp_ge_i32_e32 vcc, v0, v177
	s_nop 1
	v_cndmask_b32_e64 v177, 0, 1, vcc
	v_cndmask_b32_e64 v177, v152, v177, s[50:51]
	v_and_b32_e32 v177, 1, v177
	v_cmp_eq_u32_e32 vcc, 1, v177
	s_nop 1
	v_cndmask_b32_e32 v80, v225, v80, vcc
	v_cmp_ge_i32_e32 vcc, v0, v165
	s_nop 1
	v_cndmask_b32_e64 v165, 0, 1, vcc
	v_cndmask_b32_e64 v152, v152, v165, s[50:51]
	v_and_b32_e32 v152, 1, v152
	v_cmp_eq_u32_e32 vcc, 1, v152
	s_nop 1
	v_cndmask_b32_e32 v81, v225, v81, vcc

.LBB0_647:
	s_xor_b32 s12, s63, 1
	s_mul_i32 s12, s12, 0x8f70
	s_add_i32 s12, s12, 16
	v_lshl_add_u32 v66, v185, 1, s12
	v_add_u32_e32 v67, v66, v158
	v_add_u32_e32 v66, v66, v159
	s_waitcnt vmcnt(3)
	ds_write_b128 v67, v[82:85]
	s_waitcnt vmcnt(2)
	ds_write_b128 v66, v[86:89]
	s_waitcnt vmcnt(1)
	v_and_b32_e32 v66, 0xffff, v106
	v_add3_u32 v67, s12, v161, v160
	v_lshrrev_b32_e32 v68, 16, v106
	s_waitcnt vmcnt(0)
	v_lshl_or_b32 v66, v118, 16, v66
	v_and_or_b32 v68, v118, s91, v68
	v_add_u32_e32 v67, 0x4400, v67
	ds_write_b32 v67, v66
	ds_write_b32 v67, v68 offset:2448
	v_and_b32_e32 v66, 0xffff, v107
	v_lshrrev_b32_e32 v68, 16, v107
	v_lshl_or_b32 v66, v119, 16, v66
	v_and_or_b32 v68, v119, s91, v68
	ds_write_b32 v67, v66 offset:4896
	ds_write_b32 v67, v68 offset:7344
	v_and_b32_e32 v66, 0xffff, v108
	v_lshrrev_b32_e32 v68, 16, v108
	v_lshl_or_b32 v66, v120, 16, v66
	v_and_or_b32 v68, v120, s91, v68
	ds_write_b32 v67, v66 offset:9792
	ds_write_b32 v67, v68 offset:12240
	v_and_b32_e32 v66, 0xffff, v109
	v_lshrrev_b32_e32 v68, 16, v109
	v_lshl_or_b32 v66, v121, 16, v66
	v_and_or_b32 v68, v121, s91, v68
	ds_write_b32 v67, v66 offset:14688
	ds_write_b32 v67, v68 offset:17136

; __device__ __forceinline__ bf16_t cvt_bf16(float v) { return (bf16_t)(cvt_pk_bf16(v, 0.f) & 0xffffu); }
; template <int DQ, int TYPE>
; __device__ __forceinline__ void attn_item(PP p, int layer, int b, int h, int qt, char* lds, const int tid_, unsigned* next_ctr, volatile XLAS unsigned* slot) {
;     ...
;     A_GLOAD(A, j_lo);
;     bf16x8 qf[NKS];
;     {
;         const bf16_t* qrow = Qp + (size_t)qpos * ldq + 8 * hh;
; #pragma unroll
;         for (int ks = 0; ks < NKS; ++ks) qf[ks] = *(const bf16x8*)(qrow + 16 * ks);
;         if (TYPE == 0) {
;             const float* r64 = (const float*)(p->ws + OFF_R64) + (size_t)qpos * 64;
; #pragma unroll
;             for (int kk = 0; kk < 2; ++kk) {
;                 bf16x8 x1 = qf[8 + kk], x2 = qf[10 + kk], o1, o2;
; #pragma unroll
;                 for (int j = 0; j < 8; ++j) {
;                     const int f = 16 * kk + 8 * hh + j;
;                     const float cs = r64[2 * f], sn = r64[2 * f + 1];
;                     const float a = __uint_as_float(((unsigned)(unsigned short)x1[j]) << 16), bb = __uint_as_float(((unsigned)(unsigned short)x2[j]) << 16);
;                     o1[j] = (short)cvt_bf16(a * cs - bb * sn); o2[j] = (short)cvt_bf16(bb * cs + a * sn);
;                 }
;                 qf[8 + kk] = o1; qf[10 + kk] = o2;
;             }
;         }
.LBB0_658:
	s_and_b64 vcc, exec, s[8:9]
	s_cbranch_vccz .LBB0_385
	s_lshl_b32 s8, s47, 10
	v_readfirstlane_b32 s14, v181
	s_and_b32 s55, s8, 0x1000
	s_and_b32 s54, s48, 3
	s_bfe_u32 s48, s14, 0x20006
	s_lshl_b32 s8, s55, 11
	s_add_u32 s8, s36, s8
	s_addc_u32 s9, s37, 0
	s_lshl_b32 s13, s54, 9
	s_add_u32 s8, s8, s13
	s_addc_u32 s9, s9, 0
	s_lshl_b32 s15, s80, 7
	s_lshl_b32 s16, s48, 5
	s_mul_i32 s12, s55, 0x600
	s_lshl_b32 s13, s55, 7
	s_or_b32 s15, s16, s15
	s_add_u32 s16, s40, s12
	s_addc_u32 s17, s41, 0
	s_add_u32 s12, s44, s13
	s_addc_u32 s13, s45, 0
	s_mul_i32 s50, s54, 0x180
	s_add_u32 s16, s16, s50
	s_addc_u32 s17, s17, 0
	v_or_b32_e32 v172, s15, v154
	v_mov_b64_e32 v[2:3], s[16:17]
	s_movk_i32 s16, 0x600
	v_mov_b32_e32 v173, v1
	v_mad_u64_u32 v[2:3], s[16:17], v172, s16, v[2:3]
	v_mov_b32_e32 v147, v1
	v_lshlrev_b64 v[4:5], 8, v[172:173]
	v_lshl_add_u64 v[22:23], v[2:3], 0, v[146:147]
	v_lshlrev_b32_e32 v2, 6, v155
	v_mov_b32_e32 v3, v1
	v_lshl_add_u64 v[4:5], s[2:3], 0, v[4:5]
	global_load_dwordx4 v[10:13], v[22:23], off offset:256
	global_load_dwordx4 v[14:17], v[22:23], off offset:320
	v_lshl_add_u64 v[20:21], v[4:5], 0, v[2:3]
	global_load_dwordx2 v[24:25], v[20:21], off
	v_lshlrev_b32_e32 v18, 1, v185
	v_mov_b32_e32 v19, v1
	v_ashrrev_i32_e32 v174, 3, v181
	v_lshlrev_b64 v[2:3], 11, v[166:167]
	v_ashrrev_i32_e32 v169, 31, v168
	v_ashrrev_i32_e32 v175, 31, v174
	v_lshl_add_u64 v[176:177], s[8:9], 0, v[18:19]
	v_and_b32_e32 v0, 56, v156
	v_ashrrev_i32_e32 v171, 31, v170
	v_lshlrev_b64 v[4:5], 11, v[168:169]
	v_lshlrev_b64 v[8:9], 7, v[174:175]
	v_lshl_add_u64 v[2:3], v[176:177], 0, v[2:3]
	v_lshlrev_b32_e32 v0, 1, v0
	v_lshlrev_b64 v[6:7], 11, v[170:171]
	v_lshl_add_u64 v[4:5], v[176:177], 0, v[4:5]
	global_load_dwordx4 v[86:89], v[2:3], off
	global_load_dwordx4 v[90:93], v[4:5], off
	v_lshl_add_u64 v[2:3], s[12:13], 0, v[8:9]
	v_lshl_add_u64 v[26:27], v[176:177], 0, v[6:7]
	v_lshl_add_u64 v[2:3], v[2:3], 0, v[0:1]
	global_load_dwordx4 v[114:117], v[26:27], off offset:256
	global_load_dwordx4 v[118:121], v[2:3], off
	s_nop 0
	global_load_dwordx4 v[2:5], v[22:23], off offset:288
	global_load_dwordx4 v[82:85], v[22:23], off offset:224
	global_load_dwordx4 v[6:9], v[22:23], off offset:352
	global_load_dwordx4 v[122:125], v[26:27], off offset:2304
	global_load_dwordx4 v[94:97], v[22:23], off
	global_load_dwordx4 v[98:101], v[22:23], off offset:32
	global_load_dwordx4 v[102:105], v[22:23], off offset:64
	global_load_dwordx4 v[106:109], v[22:23], off offset:96
	global_load_dwordx4 v[110:113], v[22:23], off offset:128
	global_load_dwordx4 v[126:129], v[22:23], off offset:160
	global_load_dwordx4 v[130:133], v[22:23], off offset:192
	s_movk_i32 s8, 0x190
	v_mul_lo_u32 v189, v166, s8
	v_mul_lo_u32 v193, v168, s8
	s_movk_i32 s8, 0xc8
	v_add_u32_e32 v18, 16, v18
	s_cmpk_lt_u32 s14, 0x100
	s_cselect_b64 s[52:53], -1, 0
	s_cmpk_gt_u32 s14, 0xff
	s_movk_i32 s51, 0x190
	v_add_u32_e32 v42, v18, v189
	s_waitcnt vmcnt(17)
	v_lshlrev_b32_e32 v23, 16, v10
	s_waitcnt vmcnt(16)
	v_lshlrev_b32_e32 v22, 16, v14
	s_waitcnt vmcnt(15)
	v_pk_mul_f32 v[26:27], v[24:25], v[22:23] op_sel:[0,1] op_sel_hi:[1,0]
	v_pk_mul_f32 v[22:23], v[24:25], v[22:23]
	v_sub_f32_e32 v19, v26, v27
	v_add_f32_e32 v23, v23, v22
	v_cvt_pk_bf16_f32 v22, v19, v1
	v_cvt_pk_bf16_f32 v19, v23, v1
	global_load_dwordx2 v[24:25], v[20:21], off offset:8
	v_and_b32_e32 v27, 0xffff0000, v10
	v_and_b32_e32 v26, 0xffff0000, v14
	s_waitcnt vmcnt(13)
	v_and_b32_e32 v44, 0xffff, v116
	v_lshrrev_b32_e32 v45, 16, v116
	v_and_b32_e32 v46, 0xffff, v117
	v_lshrrev_b32_e32 v47, 16, v117
	s_waitcnt vmcnt(8)
	v_lshl_or_b32 v44, v124, 16, v44
	v_and_or_b32 v45, v124, s91, v45
	v_lshl_or_b32 v46, v125, 16, v46
	v_and_or_b32 v47, v125, s91, v47
	s_waitcnt vmcnt(0)
	v_pk_mul_f32 v[28:29], v[24:25], v[26:27] op_sel:[0,1] op_sel_hi:[1,0]
	v_pk_mul_f32 v[24:25], v[24:25], v[26:27]
	v_sub_f32_e32 v10, v28, v29
	v_add_f32_e32 v14, v24, v25
	v_cvt_pk_bf16_f32 v23, v10, v1
	v_cvt_pk_bf16_f32 v10, v14, v1
	global_load_dwordx2 v[24:25], v[20:21], off offset:16
	v_lshlrev_b32_e32 v27, 16, v11
	v_lshlrev_b32_e32 v26, 16, v15
	s_waitcnt vmcnt(0)
	v_pk_mul_f32 v[28:29], v[24:25], v[26:27] op_sel:[0,1] op_sel_hi:[1,0]
	v_pk_mul_f32 v[24:25], v[24:25], v[26:27]
	v_sub_f32_e32 v14, v28, v29
	v_add_f32_e32 v25, v24, v25
	v_cvt_pk_bf16_f32 v24, v14, v1
	v_cvt_pk_bf16_f32 v14, v25, v1
	global_load_dwordx2 v[26:27], v[20:21], off offset:24
	v_and_b32_e32 v29, 0xffff0000, v11
	v_and_b32_e32 v28, 0xffff0000, v15
	s_waitcnt vmcnt(0)
	v_pk_mul_f32 v[30:31], v[26:27], v[28:29] op_sel:[0,1] op_sel_hi:[1,0]
	v_pk_mul_f32 v[26:27], v[26:27], v[28:29]
	v_sub_f32_e32 v11, v30, v31
	v_add_f32_e32 v15, v26, v27
	v_cvt_pk_bf16_f32 v25, v11, v1
	v_cvt_pk_bf16_f32 v11, v15, v1
	global_load_dwordx2 v[26:27], v[20:21], off offset:32
	v_lshlrev_b32_e32 v29, 16, v12
	v_lshlrev_b32_e32 v28, 16, v16
	s_waitcnt vmcnt(0)
	v_pk_mul_f32 v[30:31], v[26:27], v[28:29] op_sel:[0,1] op_sel_hi:[1,0]
	v_pk_mul_f32 v[26:27], v[26:27], v[28:29]
	v_sub_f32_e32 v15, v30, v31
	v_add_f32_e32 v27, v26, v27
	v_cvt_pk_bf16_f32 v26, v15, v1
	v_cvt_pk_bf16_f32 v15, v27, v1
	global_load_dwordx2 v[28:29], v[20:21], off offset:40
	v_and_b32_e32 v31, 0xffff0000, v12
	v_and_b32_e32 v30, 0xffff0000, v16
	s_waitcnt vmcnt(0)
	v_pk_mul_f32 v[32:33], v[28:29], v[30:31] op_sel:[0,1] op_sel_hi:[1,0]
	v_pk_mul_f32 v[28:29], v[28:29], v[30:31]
	v_sub_f32_e32 v12, v32, v33
	v_add_f32_e32 v16, v28, v29
	v_cvt_pk_bf16_f32 v27, v12, v1
	v_cvt_pk_bf16_f32 v12, v16, v1
	global_load_dwordx2 v[28:29], v[20:21], off offset:48
	v_lshlrev_b32_e32 v31, 16, v13
	v_lshlrev_b32_e32 v30, 16, v17
	s_waitcnt vmcnt(0)
; __device__ __forceinline__ bf16_t cvt_bf16(float v) { return (bf16_t)(cvt_pk_bf16(v, 0.f) & 0xffffu); }
; template <int DQ, int TYPE>
; __device__ __forceinline__ void attn_item(PP p, int layer, int b, int h, int qt, char* lds, const int tid_, unsigned* next_ctr, volatile XLAS unsigned* slot) {
;     ...
;             for (int kk = 0; kk < 2; ++kk) {
;                 bf16x8 x1 = qf[8 + kk], x2 = qf[10 + kk], o1, o2;
; #pragma unroll
;                 for (int j = 0; j < 8; ++j) {
;                     const int f = 16 * kk + 8 * hh + j;
;                     const float cs = r64[2 * f], sn = r64[2 * f + 1];
;                     const float a = __uint_as_float(((unsigned)(unsigned short)x1[j]) << 16), bb = __uint_as_float(((unsigned)(unsigned short)x2[j]) << 16);
;                     o1[j] = (short)cvt_bf16(a * cs - bb * sn); o2[j] = (short)cvt_bf16(bb * cs + a * sn);
;                 }
;                 qf[8 + kk] = o1; qf[10 + kk] = o2;
;             }
;         }
	v_pk_mul_f32 v[32:33], v[28:29], v[30:31] op_sel:[0,1] op_sel_hi:[1,0]
	v_pk_mul_f32 v[28:29], v[28:29], v[30:31]
	v_sub_f32_e32 v16, v32, v33
	v_add_f32_e32 v29, v28, v29
	v_cvt_pk_bf16_f32 v28, v16, v1
	v_cvt_pk_bf16_f32 v16, v29, v1
	global_load_dwordx2 v[30:31], v[20:21], off offset:56
	v_and_b32_e32 v33, 0xffff0000, v13
	v_and_b32_e32 v32, 0xffff0000, v17
	s_waitcnt vmcnt(0)
	v_pk_mul_f32 v[34:35], v[30:31], v[32:33] op_sel:[0,1] op_sel_hi:[1,0]
	v_pk_mul_f32 v[30:31], v[30:31], v[32:33]
	v_sub_f32_e32 v13, v34, v35
	v_add_f32_e32 v17, v30, v31
	v_cvt_pk_bf16_f32 v30, v13, v1
	v_cvt_pk_bf16_f32 v17, v17, v1
	global_load_dwordx2 v[32:33], v[20:21], off offset:128
	v_lshlrev_b32_e32 v35, 16, v2
	v_lshlrev_b32_e32 v34, 16, v6
	s_waitcnt vmcnt(0)
	v_pk_mul_f32 v[36:37], v[32:33], v[34:35] op_sel:[0,1] op_sel_hi:[1,0]
	v_pk_mul_f32 v[32:33], v[32:33], v[34:35]
	v_sub_f32_e32 v13, v36, v37
	v_add_f32_e32 v31, v32, v33
	v_cvt_pk_bf16_f32 v29, v13, v1
	v_cvt_pk_bf16_f32 v13, v31, v1
	global_load_dwordx2 v[32:33], v[20:21], off offset:136
	v_and_b32_e32 v35, 0xffff0000, v2
	v_and_b32_e32 v34, 0xffff0000, v6
	s_waitcnt vmcnt(0)
	v_pk_mul_f32 v[36:37], v[32:33], v[34:35] op_sel:[0,1] op_sel_hi:[1,0]
	v_pk_mul_f32 v[32:33], v[32:33], v[34:35]
	v_sub_f32_e32 v2, v36, v37
	v_add_f32_e32 v6, v32, v33
	v_cvt_pk_bf16_f32 v31, v2, v1
	v_cvt_pk_bf16_f32 v2, v6, v1
	global_load_dwordx2 v[32:33], v[20:21], off offset:144
	v_lshlrev_b32_e32 v35, 16, v3
	v_lshlrev_b32_e32 v34, 16, v7
	s_waitcnt vmcnt(0)
	v_pk_mul_f32 v[36:37], v[32:33], v[34:35] op_sel:[0,1] op_sel_hi:[1,0]
	v_pk_mul_f32 v[32:33], v[32:33], v[34:35]
	v_sub_f32_e32 v6, v36, v37
	v_add_f32_e32 v33, v32, v33
	v_cvt_pk_bf16_f32 v32, v6, v1
	v_cvt_pk_bf16_f32 v6, v33, v1
	global_load_dwordx2 v[34:35], v[20:21], off offset:152
	v_and_b32_e32 v37, 0xffff0000, v3
	v_and_b32_e32 v36, 0xffff0000, v7
	s_waitcnt vmcnt(0)
	v_pk_mul_f32 v[38:39], v[34:35], v[36:37] op_sel:[0,1] op_sel_hi:[1,0]
	v_pk_mul_f32 v[34:35], v[34:35], v[36:37]
	v_sub_f32_e32 v3, v38, v39
	v_add_f32_e32 v7, v34, v35
	v_cvt_pk_bf16_f32 v33, v3, v1
	v_cvt_pk_bf16_f32 v3, v7, v1
	global_load_dwordx2 v[34:35], v[20:21], off offset:160
	v_lshlrev_b32_e32 v37, 16, v4
	v_lshlrev_b32_e32 v36, 16, v8
	s_waitcnt vmcnt(0)
	v_pk_mul_f32 v[38:39], v[34:35], v[36:37] op_sel:[0,1] op_sel_hi:[1,0]
	v_pk_mul_f32 v[34:35], v[34:35], v[36:37]
	v_sub_f32_e32 v7, v38, v39
	v_add_f32_e32 v35, v34, v35
	v_cvt_pk_bf16_f32 v34, v7, v1
	v_cvt_pk_bf16_f32 v7, v35, v1
	global_load_dwordx2 v[36:37], v[20:21], off offset:168
	v_and_b32_e32 v39, 0xffff0000, v4
	v_and_b32_e32 v38, 0xffff0000, v8
	s_waitcnt vmcnt(0)
	v_pk_mul_f32 v[40:41], v[36:37], v[38:39] op_sel:[0,1] op_sel_hi:[1,0]
	v_pk_mul_f32 v[36:37], v[36:37], v[38:39]
	v_sub_f32_e32 v4, v40, v41
	v_add_f32_e32 v8, v36, v37
	v_cvt_pk_bf16_f32 v35, v4, v1
	v_cvt_pk_bf16_f32 v4, v8, v1
	global_load_dwordx2 v[36:37], v[20:21], off offset:176
	v_lshlrev_b32_e32 v39, 16, v5
	v_lshlrev_b32_e32 v38, 16, v9
	s_waitcnt vmcnt(0)
	v_pk_mul_f32 v[40:41], v[36:37], v[38:39] op_sel:[0,1] op_sel_hi:[1,0]
	v_pk_mul_f32 v[36:37], v[36:37], v[38:39]
	v_sub_f32_e32 v8, v40, v41
	v_add_f32_e32 v37, v36, v37
	v_cvt_pk_bf16_f32 v36, v8, v1
	v_cvt_pk_bf16_f32 v8, v37, v1
	global_load_dwordx2 v[20:21], v[20:21], off offset:184
	v_mul_u32_u24_e32 v37, 15, v185
	v_lshlrev_b32_e32 v38, 2, v166
	v_mul_lo_u32 v39, v174, s8
	v_add3_u32 v37, v18, v37, v38
	v_lshlrev_b32_e32 v194, 1, v39
	v_and_b32_e32 v38, 0xffff, v114
	v_lshrrev_b32_e32 v39, 16, v114
	v_and_b32_e32 v40, 0xffff, v115
	v_lshrrev_b32_e32 v41, 16, v115
	v_lshl_or_b32 v48, v122, 16, v38
	v_and_or_b32 v49, v122, s91, v39
	v_and_b32_e32 v39, 0xffff0000, v5
	v_and_b32_e32 v38, 0xffff0000, v9
	s_cselect_b64 s[8:9], -1, 0
	v_lshl_or_b32 v50, v123, 16, v40
	v_and_or_b32 v51, v123, s91, v41
	s_and_b64 vcc, exec, s[8:9]
	v_add_u32_e32 v18, v18, v193
	v_add3_u32 v43, 16, v194, v0
	v_add_u32_e32 v37, 0x6400, v37
	s_waitcnt vmcnt(0)
	v_pk_mul_f32 v[40:41], v[20:21], v[38:39] op_sel:[0,1] op_sel_hi:[1,0]
	v_pk_mul_f32 v[20:21], v[20:21], v[38:39]
	v_sub_f32_e32 v5, v40, v41
	v_add_f32_e32 v20, v20, v21
	v_cvt_pk_bf16_f32 v9, v5, v1
	v_cvt_pk_bf16_f32 v5, v20, v1
	ds_write_b128 v42, v[86:89]
	ds_write_b128 v18, v[90:93]
	ds_write_b128 v43, v[118:121] offset:256
	ds_write_b32 v37, v48
	ds_write_b32 v37, v49 offset:2448
	ds_write_b32 v37, v50 offset:4896
	ds_write_b32 v37, v51 offset:7344
	ds_write_b32 v37, v44 offset:9792
	ds_write_b32 v37, v45 offset:12240
	ds_write_b32 v37, v46 offset:14688
	ds_write_b32 v37, v47 offset:17136
	s_waitcnt lgkmcnt(0)
	s_barrier
	s_cbranch_vccnz .LBB0_661
	s_setprio 2
; template <int DQ, int TYPE>
; __device__ __forceinline__ void attn_item(PP p, int layer, int b, int h, int qt, char* lds, const int tid_, unsigned* next_ctr, volatile XLAS unsigned* slot) {
;     ...
;     f32x16 O[4];
; #pragma unroll
;     for (int md = 0; md < 4; ++md)
; #pragma unroll
;         for (int i = 0; i < 16; ++i) O[md][i] = 0.f;
;     float m_run = -1e30f, l_run = 0.f;
;     if (TYPE == 2 && kh == 0) { m_run = p->sinks[layer * 8 + h] * LOG2E; l_run = (hh == 0) ? 1.f : 0.f; }
;     constexpr int GK = (DQ == 192) ? 3 : 4, NG = NKS / GK;
;     A_LSTORE(A, 0); __syncthreads();
;     if (kh == 0) __builtin_amdgcn_s_setprio(2);
; #pragma unroll 1
;     for (int j = j_lo; j <= j_hi; ++j) {
;         const int buf = (j - j_lo) & 1;
;         if (j < j_hi) A_GLOAD(A, j + 1);
;         int mode = 0;
;         if (TYPE == 2) mode = 2;
;         else if (TYPE == 1 && (j >> 2) < own) mode = 3;
;         else if (j >= 2 * qt) mode = 1;
;         const int kbase_pos = 64 * j + 32 * kh;
.LBB0_661:
	s_ashr_i32 s56, s14, 8
	v_lshl_add_u64 v[190:191], s[12:13], 0, v[0:1]
	s_lshl_b32 s17, s56, 5
	s_mov_b32 s12, 0x5040100
	v_or_b32_e32 v18, s17, v154
	v_perm_b32 v140, v35, v34, s12
	v_mov_b32_e32 v34, v1
	v_mov_b32_e32 v35, v1
	v_mov_b32_e32 v48, v1
	v_mov_b32_e32 v49, v1
	v_mul_lo_u32 v196, v18, s51
	v_perm_b32 v137, v30, v28, s12
	v_perm_b32 v136, v27, v26, s12
	v_perm_b32 v135, v25, v24, s12
	v_perm_b32 v134, v23, v22, s12
	v_perm_b32 v141, v9, v36, s12
	v_perm_b32 v139, v33, v32, s12
	v_perm_b32 v138, v31, v29, s12
	v_perm_b32 v145, v17, v16, s12
	v_perm_b32 v144, v12, v15, s12
	v_perm_b32 v143, v11, v14, s12
	v_perm_b32 v142, v10, v19, s12
	v_perm_b32 v149, v5, v8, s12
	v_perm_b32 v148, v4, v7, s12
	v_perm_b32 v147, v3, v6, s12
	v_perm_b32 v146, v2, v13, s12
	s_lshl_b32 s12, s49, 1
	v_mov_b32_e32 v36, v1
	v_mov_b32_e32 v37, v1
	v_mov_b32_e32 v38, v1
	v_mov_b32_e32 v39, v1
	v_mov_b32_e32 v40, v1
	v_mov_b32_e32 v41, v1
	v_mov_b32_e32 v42, v1
	v_mov_b32_e32 v43, v1
	v_mov_b32_e32 v44, v1
	v_mov_b32_e32 v45, v1
	v_mov_b32_e32 v46, v1
	v_mov_b32_e32 v47, v1
	v_mov_b64_e32 v[64:65], v[48:49]
	v_mov_b64_e32 v[2:3], v[34:35]
	v_mov_b64_e32 v[18:19], v[34:35]
	v_mul_u32_u24_e32 v195, 17, v185
	s_lshl_b32 s16, s80, 1
	s_or_b32 s50, s15, 31
	v_and_b32_e32 v244, 7, v154
	v_lshrrev_b32_e32 v245, 3, v154
	v_mad_u32_u24 v244, v244, 18, v245
	v_mul_u32_u24_e32 v197, 0x88, v244
	v_lshlrev_b32_e32 v187, 2, v155
	s_sub_i32 s49, 64, s12
	s_mov_b32 s51, 0
	v_mov_b32_e32 v199, 0
	v_mov_b32_e32 v205, 0xf149f2ca
	v_lshlrev_b32_e32 v198, 1, v153
	s_mov_b32 s57, s17
	v_mov_b64_e32 v[62:63], v[46:47]
	v_mov_b64_e32 v[60:61], v[44:45]
	v_mov_b64_e32 v[58:59], v[42:43]
	v_mov_b64_e32 v[56:57], v[40:41]
	v_mov_b64_e32 v[54:55], v[38:39]
	v_mov_b64_e32 v[52:53], v[36:37]
	v_mov_b64_e32 v[50:51], v[34:35]
	v_mov_b64_e32 v[4:5], v[36:37]
	v_mov_b64_e32 v[6:7], v[38:39]
	v_mov_b64_e32 v[8:9], v[40:41]
	v_mov_b64_e32 v[10:11], v[42:43]
	v_mov_b64_e32 v[12:13], v[44:45]
	v_mov_b64_e32 v[14:15], v[46:47]
	v_mov_b64_e32 v[16:17], v[48:49]
	v_mov_b64_e32 v[20:21], v[36:37]
	v_mov_b64_e32 v[22:23], v[38:39]
	v_mov_b64_e32 v[24:25], v[40:41]
	v_mov_b64_e32 v[26:27], v[42:43]
	v_mov_b64_e32 v[28:29], v[44:45]
	v_mov_b64_e32 v[30:31], v[46:47]
	v_mov_b64_e32 v[32:33], v[48:49]
	s_cmp_le_u32 s51, s16
	s_cselect_b64 s[12:13], -1, 0
	s_cmp_gt_u32 s51, s16
	s_cbranch_scc1 .LBB0_664
	s_branch .LBB0_663

; template <int DQ, int TYPE>
; __device__ __forceinline__ void attn_item(PP p, int layer, int b, int h, int qt, char* lds, const int tid_, unsigned* next_ctr, volatile XLAS unsigned* slot) {
;     ...
;         if (!skip) {
;             const bf16_t* Ks = (const bf16_t*)(lds + buf * STAGE); const bf16_t* Vt = (const bf16_t*)(lds + buf * STAGE + KBYTES);
;             f32x16 sacc;
; #pragma unroll
;             for (int i = 0; i < 16; ++i) sacc[i] = 0.f;
;             const bf16_t* kb_ = Ks + (32 * kh + r) * KLD + 8 * hh;
;             bf16x8 kf[2][GK];
; #pragma unroll
;             for (int i = 0; i < GK; ++i) kf[0][i] = *(const bf16x8*)(kb_ + 16 * i);
; #pragma unroll
;             for (int g = 0; g < NG; ++g) {
;                 if (g + 1 < NG) {
; #pragma unroll
;                     for (int i = 0; i < GK; ++i) kf[(g + 1) & 1][i] = *(const bf16x8*)(kb_ + 16 * ((g + 1) * GK + i));
;                 }
;                 __builtin_amdgcn_sched_barrier(0);
; #pragma unroll
;                 for (int i = 0; i < GK; ++i) sacc = __builtin_amdgcn_mfma_f32_32x32x16_bf16(kf[g & 1][i], qf[g * GK + i], sacc, 0, 0, 0);
;                 __builtin_amdgcn_sched_barrier(0);
;             }
;             const bf16_t* vb0 = Vt + r * VLD + 32 * kh + 4 * hh;
;             u32x2 vf[2][4][2];
; #pragma unroll
;             for (int md = 0; md < 4; ++md) { vf[0][md][0] = *(const u32x2*)(vb0 + md * 32 * VLD); vf[0][md][1] = *(const u32x2*)(vb0 + md * 32 * VLD + 8); }
;             if (mode != 0) {
;                 const bool selbit = (qmask >> (j >> 2)) & 1u;
; #pragma unroll
;                 for (int i = 0; i < 16; ++i) {
;                     const int kpos = kbase_pos + 8 * (i >> 2) + 4 * hh + (i & 3);
;                     const int dd = qpos - kpos;
;                     bool ok;
;                     if (mode == 1) ok = dd >= 0; else if (mode == 2) ok = (dd >= 0 && dd < 128); else ok = selbit;
;                     if (!ok) sacc[i] = -INFINITY;
;                 }
.LBB0_664:
	s_and_b32 s58, s51, 1
	s_cmp_ge_u32 s51, s16
	s_cselect_b64 s[14:15], -1, 0
	s_cmp_gt_i32 s57, s50
	s_cselect_b64 s[60:61], -1, 0
	s_and_b64 s[60:61], s[14:15], s[60:61]
	s_and_b64 vcc, exec, s[60:61]
	s_cbranch_vccnz .LBB0_670
	s_mul_i32 s59, s58, 0xaf70
	s_add_i32 s59, s59, 16
	v_add3_u32 v192, s59, v196, v198
	ds_read_b128 v[66:69], v192
	ds_read_b128 v[150:153], v192 offset:32
	ds_read_b128 v[154:157], v192 offset:64
	ds_read_b128 v[158:161], v192 offset:96
	ds_read_b128 v[162:165], v192 offset:128
	ds_read_b128 v[200:203], v192 offset:160
	s_waitcnt lgkmcnt(5)
	v_mfma_f32_32x32x16_bf16 v[66:81], v[66:69], v[94:97], 0
	s_waitcnt lgkmcnt(4)
	v_mfma_f32_32x32x16_bf16 v[66:81], v[150:153], v[98:101], v[66:81]
	s_waitcnt lgkmcnt(3)
	v_mfma_f32_32x32x16_bf16 v[66:81], v[154:157], v[102:105], v[66:81]
	ds_read_b128 v[150:153], v192 offset:192
	ds_read_b128 v[154:157], v192 offset:224
	ds_read_b128 v[206:209], v192 offset:256
	s_waitcnt lgkmcnt(5)
	v_mfma_f32_32x32x16_bf16 v[66:81], v[158:161], v[106:109], v[66:81]
	s_waitcnt lgkmcnt(4)
	v_mfma_f32_32x32x16_bf16 v[66:81], v[162:165], v[110:113], v[66:81]
	s_waitcnt lgkmcnt(3)
	v_mfma_f32_32x32x16_bf16 v[66:81], v[200:203], v[126:129], v[66:81]
	ds_read_b128 v[158:161], v192 offset:288
	ds_read_b128 v[210:213], v192 offset:320
	ds_read_b128 v[240:243], v192 offset:352
	s_waitcnt lgkmcnt(5)
	v_mfma_f32_32x32x16_bf16 v[66:81], v[150:153], v[130:133], v[66:81]
	s_waitcnt lgkmcnt(4)
	v_mfma_f32_32x32x16_bf16 v[66:81], v[154:157], v[82:85], v[66:81]
	s_waitcnt lgkmcnt(3)
	v_mfma_f32_32x32x16_bf16 v[66:81], v[206:209], v[134:137], v[66:81]
	s_waitcnt lgkmcnt(2)
	v_mfma_f32_32x32x16_bf16 v[66:81], v[158:161], v[138:141], v[66:81]
	s_lshl_b32 s60, s17, 1
	s_add_i32 s60, s60, s59
	v_lshlrev_b32_e32 v150, 1, v187
	v_add3_u32 v150, s60, v197, v150
	v_add_u32_e32 v203, 0x6000, v150
	v_add_u32_e32 v201, 0x6120, v150
	v_add_u32_e32 v204, 0x6240, v150
	s_waitcnt lgkmcnt(1)
	v_mfma_f32_32x32x16_bf16 v[66:81], v[210:213], v[142:145], v[66:81]
	v_add_u32_e32 v202, 0x6360, v150
	ds_read2_b64 v[162:165], v203 offset0:128 offset1:130
	ds_read2_b64 v[158:161], v201 offset0:160 offset1:162
	ds_read2_b64 v[154:157], v204 offset0:192 offset1:194
	ds_read2_b64 v[150:153], v202 offset0:224 offset1:226
	s_andn2_b64 vcc, exec, s[14:15]
	s_waitcnt lgkmcnt(4)
	v_mfma_f32_32x32x16_bf16 v[66:81], v[240:243], v[146:149], v[66:81]
	s_cbranch_vccnz .LBB0_667
	v_add_u32_e32 v192, s57, v187
	v_cmp_gt_i32_e32 vcc, v172, v192
	v_add_u32_e32 v200, 2, v192
	s_nop 7
	v_cndmask_b32_e32 v67, v225, v67, vcc
	v_cmp_ge_i32_e32 vcc, v172, v192
	s_nop 1
	v_cndmask_b32_e32 v66, v225, v66, vcc
	v_cmp_ge_i32_e32 vcc, v172, v200
	v_add_u32_e32 v200, 3, v192
	s_nop 0
	v_cndmask_b32_e32 v68, v225, v68, vcc
	v_cmp_ge_i32_e32 vcc, v172, v200
	v_add_u32_e32 v200, 8, v192
	s_nop 0
	v_cndmask_b32_e32 v69, v225, v69, vcc
	v_cmp_ge_i32_e32 vcc, v172, v200
	v_add_u32_e32 v200, 9, v192
	s_nop 0
	v_cndmask_b32_e32 v70, v225, v70, vcc
	v_cmp_ge_i32_e32 vcc, v172, v200
	v_add_u32_e32 v200, 10, v192
	s_nop 0
	v_cndmask_b32_e32 v71, v225, v71, vcc
	v_cmp_ge_i32_e32 vcc, v172, v200
	v_add_u32_e32 v200, 11, v192
	s_nop 0
	v_cndmask_b32_e32 v72, v225, v72, vcc
	v_cmp_ge_i32_e32 vcc, v172, v200
	v_add_u32_e32 v200, 16, v192
	s_nop 0
	v_cndmask_b32_e32 v73, v225, v73, vcc
	v_cmp_ge_i32_e32 vcc, v172, v200
	v_add_u32_e32 v200, 17, v192
	s_nop 0
	v_cndmask_b32_e32 v74, v225, v74, vcc
	v_cmp_ge_i32_e32 vcc, v172, v200
	v_add_u32_e32 v200, 18, v192
	s_nop 0
	v_cndmask_b32_e32 v75, v225, v75, vcc
	v_cmp_ge_i32_e32 vcc, v172, v200
	v_add_u32_e32 v200, 19, v192
	s_nop 0
	v_cndmask_b32_e32 v76, v225, v76, vcc
	v_cmp_ge_i32_e32 vcc, v172, v200
	v_add_u32_e32 v200, 24, v192
	s_nop 0
	v_cndmask_b32_e32 v77, v225, v77, vcc
	v_cmp_ge_i32_e32 vcc, v172, v200
	v_add_u32_e32 v200, 25, v192
	s_nop 0
	v_cndmask_b32_e32 v78, v225, v78, vcc
	v_cmp_ge_i32_e32 vcc, v172, v200
	v_add_u32_e32 v200, 26, v192
	v_add_u32_e32 v192, 27, v192
	v_cndmask_b32_e32 v79, v225, v79, vcc
	v_cmp_ge_i32_e32 vcc, v172, v200
	s_nop 1
	v_cndmask_b32_e32 v80, v225, v80, vcc
	v_cmp_ge_i32_e32 vcc, v172, v192
	s_nop 1
	v_cndmask_b32_e32 v81, v225, v81, vcc

; template <int DQ, int TYPE>
; __device__ __forceinline__ void attn_item(PP p, int layer, int b, int h, int qt, char* lds, const int tid_, unsigned* next_ctr, volatile XLAS unsigned* slot) {
;     ...
;         if (j < j_hi) A_LSTORE(A, buf ^ 1);
.LBB0_671:
	s_xor_b32 s12, s58, 1
	s_mul_i32 s12, s12, 0xaf70
	s_add_i32 s12, s12, 16
	v_lshl_add_u32 v66, v185, 1, s12
	v_add_u32_e32 v67, v66, v189
	v_add_u32_e32 v66, v66, v193
	s_waitcnt vmcnt(4)
	ds_write_b128 v67, v[86:89]
	s_waitcnt vmcnt(3)
	ds_write_b128 v66, v[90:93]
	v_add3_u32 v66, s12, v194, v0
	v_lshlrev_b32_e32 v67, 1, v170
	s_waitcnt vmcnt(2)
	ds_write_b128 v66, v[118:121] offset:256
	s_waitcnt vmcnt(1)
	v_and_b32_e32 v66, 0xffff, v114
	v_add3_u32 v67, s12, v195, v67
	v_lshrrev_b32_e32 v68, 16, v114
	s_waitcnt vmcnt(0)
	v_lshl_or_b32 v66, v122, 16, v66
	v_and_or_b32 v68, v122, s91, v68
	v_add_u32_e32 v67, 0x6400, v67
	ds_write_b32 v67, v66
	ds_write_b32 v67, v68 offset:2448
	v_and_b32_e32 v66, 0xffff, v115
	v_lshrrev_b32_e32 v68, 16, v115
	v_lshl_or_b32 v66, v123, 16, v66
	v_and_or_b32 v68, v123, s91, v68
	ds_write_b32 v67, v66 offset:4896
	ds_write_b32 v67, v68 offset:7344
	v_and_b32_e32 v66, 0xffff, v116
	v_lshrrev_b32_e32 v68, 16, v116
	v_lshl_or_b32 v66, v124, 16, v66
	v_and_or_b32 v68, v124, s91, v68
	ds_write_b32 v67, v66 offset:9792
	ds_write_b32 v67, v68 offset:12240
	v_and_b32_e32 v66, 0xffff, v117
	v_lshrrev_b32_e32 v68, 16, v117
	v_lshl_or_b32 v66, v125, 16, v66
	v_and_or_b32 v68, v125, s91, v68
	ds_write_b32 v67, v66 offset:14688
	ds_write_b32 v67, v68 offset:17136
